# NA attention unit prologue: bias-table fill loop (load/wait/ds_write x4 per thread) replaced by four loads with immediate offsets and one wait; on top of v_micro2
# speedup vs baseline: 1.0011x; 1.0011x over previous
.LBB0_1017:
	s_or_b64 exec, exec, s[4:5]
	s_add_i32 s36, 0, 0x16800
	s_mov_b64 s[4:5], src_shared_base
	s_cmp_lg_u32 s36, -1
	s_cselect_b32 s4, s36, 0
	s_cselect_b32 s5, s5, 0
	v_mov_b32_e32 v4, s4
	v_mov_b32_e32 v5, s5
	s_waitcnt vmcnt(0) lgkmcnt(0)
	s_barrier
	flat_load_dword v2, v[4:5] sc0 sc1
	s_waitcnt vmcnt(0)
	s_mov_b64 s[4:5], -1
	s_waitcnt lgkmcnt(0)
	v_readfirstlane_b32 s17, v2
	s_cmpk_gt_i32 s17, 0x7f
	s_cbranch_scc1 .LBB0_1012
	v_mov_b32_e32 v4, v0
	s_movk_i32 s6, 0x780
	s_bfe_u32 s37, s17, 0x20002
	s_mov_b64 s[4:5], s[0:1]
	v_cmp_gt_i32_e32 vcc, s6, v4
	s_and_saveexec_b64 s[6:7], vcc
	s_cbranch_execz .LBB0_1023
	s_load_dwordx2 s[4:5], s[4:5], 0xa8
	v_readlane_b32 s8, v255, 32
	s_or_b32 s8, s37, s8
	v_and_b32_e32 v2, 0x7f, v4
	s_mulk_i32 s8, 0x744
	v_subrev_u32_e32 v5, 48, v2
	s_waitcnt lgkmcnt(0)
	s_add_u32 s8, s4, s8
	v_readlane_b32 s4, v255, 18
	s_addc_u32 s9, s5, 0
	v_cmp_gt_u32_e32 vcc, 31, v5
	v_lshl_add_u32 v5, v4, 2, s4
	v_ashrrev_i32_e32 v7, 7, v4
	v_mul_lo_u32 v8, v7, 31
	v_ashrrev_i32_e32 v9, 31, v8
	v_lshl_add_u64 v[8:9], v[8:9], 0, v[2:3]
	v_lshl_add_u64 v[8:9], v[8:9], 2, s[8:9]
	v_mov_b32_e32 v7, 0
	v_mov_b32_e32 v6, 0
	v_mov_b32_e32 v2, 0
	s_mov_b64 s[14:15], exec
	s_and_b64 exec, exec, vcc
	global_load_dword v7, v[8:9], off offset:-192
	global_load_dword v6, v[8:9], off offset:304
	global_load_dword v2, v[8:9], off offset:800
	v_cmp_gt_u32_e32 vcc, 0x180, v4
	s_mov_b64 s[4:5], vcc
	s_and_b64 exec, exec, vcc
	global_load_dword v8, v[8:9], off offset:1296
	s_mov_b64 exec, s[14:15]
	s_waitcnt vmcnt(0)
	v_cndmask_b32_e64 v8, 0, v8, s[4:5]
	v_mul_f32_e32 v7, 0x413504f3, v7
	v_mul_f32_e32 v6, 0x413504f3, v6
	v_mul_f32_e32 v2, 0x413504f3, v2
	v_mul_f32_e32 v8, 0x413504f3, v8
	ds_write_b32 v5, v7
	ds_write_b32 v5, v6 offset:2048
	ds_write_b32 v5, v2 offset:4096
	v_cmp_gt_u32_e32 vcc, 0x180, v4
	s_and_saveexec_b64 s[4:5], vcc
	ds_write_b32 v5, v8 offset:6144
	s_or_b64 exec, exec, s[4:5]
	v_and_b32_e32 v2, 0x7f, v4
